# phase G gemm80 K loop: LDS stage released mid-iteration, tile k+2 prefetched, counted vmcnt (2 tiles in flight)
# speedup vs baseline: 1.0074x; 1.0031x over previous
.LBB0_86:
	s_or_b64 exec, exec, s[42:43]
	s_add_i32 s24, s51, s0
	v_lshrrev_b32_e32 v1, 2, v4
	s_ashr_i32 s25, s24, 31
	v_lshlrev_b32_e32 v0, 5, v2
	v_and_b32_e32 v1, 8, v1
	v_and_b32_e32 v6, 3, v6
	s_lshl_b64 s[24:25], s[24:25], 20
	v_or3_b32 v0, v0, v1, v6
	s_add_u32 s24, s49, s24
	v_ashrrev_i32_e32 v1, 31, v0
	v_lshlrev_b32_e32 v8, 3, v7
	s_addc_u32 s25, s50, s25
	v_lshlrev_b64 v[0:1], 10, v[0:1]
	v_lshl_add_u64 v[6:7], s[24:25], 0, v[0:1]
	v_lshlrev_b32_e32 v8, 1, v8
	v_mov_b32_e32 v9, v129
	s_movk_i32 s26, 0xc00
	v_lshl_add_u64 v[6:7], v[6:7], 0, v[8:9]
	v_mad_u64_u32 v[8:9], s[24:25], v2, s26, v[94:95]
	v_add_u32_e32 v9, 0x4000, v8
	v_lshlrev_b32_e32 v102, 12, v2
	v_readfirstlane_b32 s24, v9
	s_mov_b32 m0, s24
	s_mov_b64 s[24:25], 0x4000
	v_add_u32_e32 v9, 0x4400, v8
	v_lshl_add_u64 v[10:11], v[6:7], 0, s[24:25]
	v_readfirstlane_b32 s24, v9
	v_add_u32_e32 v9, 0x4800, v8
	global_load_lds_dwordx4 v[6:7], off
	s_mov_b32 m0, s24
	v_readfirstlane_b32 s24, v9
	global_load_lds_dwordx4 v[10:11], off
	s_mov_b32 m0, s24
	s_mov_b64 s[24:25], 0x5000
	v_add_u32_e32 v8, 0x4c00, v8
	v_lshl_add_u64 v[10:11], v[6:7], 0, s[44:45]
	v_lshl_add_u64 v[6:7], v[6:7], 0, s[24:25]
	v_readfirstlane_b32 s24, v8
	global_load_lds_dwordx4 v[10:11], off
	s_mov_b32 m0, s24
	v_add_u32_e32 v2, v5, v3
	global_load_lds_dwordx4 v[6:7], off
	v_and_b32_e32 v6, 7, v4
	v_lshlrev_b32_e32 v7, 7, v4
	v_lshlrev_b32_e32 v6, 4, v6
	v_mad_i64_i32 v[2:3], s[24:25], v2, s26, 0
	v_or_b32_e32 v0, v0, v128
	v_and_b32_e32 v7, 0x780, v7
	v_bitop3_b32 v4, v6, v4, 48 bitop3:0x78
	v_or_b32_e32 v2, v2, v128
	v_lshl_add_u64 v[98:99], s[40:41], 0, v[0:1]
	v_mov_b32_e32 v0, 0
	v_or_b32_e32 v45, v4, v7
	v_bitop3_b32 v95, v4, 64, v7 bitop3:0x36
	v_add_u32_e32 v103, 0x4000, v102
	s_movk_i32 s84, 0xc00
	v_lshl_add_u64 v[96:97], s[30:31], 0, v[2:3]
	s_mov_b32 s25, 0
	s_mov_b64 s[42:43], 0
	s_mov_b32 s24, 0
	v_mov_b32_e32 v1, v0
	v_mov_b32_e32 v2, v0
	v_mov_b32_e32 v3, v0
	v_mov_b32_e32 v4, v0
	v_mov_b32_e32 v5, v0
	v_mov_b32_e32 v6, v0
	v_mov_b32_e32 v7, v0
	v_mov_b32_e32 v8, v0
	v_mov_b32_e32 v9, v0
	v_mov_b32_e32 v10, v0
	v_mov_b32_e32 v11, v0
	v_mov_b32_e32 v12, v0
	v_mov_b32_e32 v13, v0
	v_mov_b32_e32 v14, v0
	v_mov_b32_e32 v15, v0
	v_mov_b32_e32 v16, v0
	v_mov_b32_e32 v17, v0
	v_mov_b32_e32 v18, v0
	v_mov_b32_e32 v19, v0
	v_mov_b32_e32 v20, v0
	v_mov_b32_e32 v21, v0
	v_mov_b32_e32 v22, v0
	v_mov_b32_e32 v23, v0
	v_mov_b32_e32 v24, v0
	v_mov_b32_e32 v25, v0
	v_mov_b32_e32 v26, v0
	v_mov_b32_e32 v27, v0
	v_mov_b32_e32 v28, v0
	v_mov_b32_e32 v29, v0
	v_mov_b32_e32 v30, v0
	v_mov_b32_e32 v31, v0
	v_mov_b32_e32 v32, v0
	v_mov_b32_e32 v33, v0
	v_mov_b32_e32 v34, v0
	v_mov_b32_e32 v35, v0
	v_mov_b32_e32 v36, v0
	v_mov_b32_e32 v37, v0
	v_mov_b32_e32 v38, v0
	v_mov_b32_e32 v39, v0
	s_mov_b32 s28, 0x8000
	v_add_u32_e32 v104, s28, v94
	v_lshl_add_u64 v[100:101], v[96:97], 0, s[42:43]
	s_mov_b64 s[44:45], 0xc65c080
	v_lshl_add_u64 v[106:107], v[100:101], 0, s[44:45]
	v_readfirstlane_b32 s44, v104
	s_mov_b32 m0, s44
	s_mov_b64 s[44:45], 0xc674080
	v_add_u32_e32 v105, 0x1000, v104
	global_load_lds_dwordx4 v[106:107], off
	v_lshl_add_u64 v[106:107], v[100:101], 0, s[44:45]
	v_readfirstlane_b32 s44, v105
	s_mov_b32 m0, s44
	s_nop 0
	global_load_lds_dwordx4 v[106:107], off
	s_and_saveexec_b64 s[44:45], s[36:37]
	s_cbranch_execz .Lg80p_noA3
	s_mov_b64 s[52:53], 0xc68c080
	v_add_u32_e32 v104, 0x2000, v104
	v_lshl_add_u64 v[100:101], v[100:101], 0, s[52:53]
	v_readfirstlane_b32 s52, v104
	s_mov_b32 m0, s52
	s_nop 0
	global_load_lds_dwordx4 v[100:101], off

.LBB0_89:
	s_cmp_lt_u32 s24, 7
	s_cbranch_scc1 .Lg80_cnt
	s_waitcnt vmcnt(0)
	s_branch .Lg80_wd
.Lg80_cnt:
	s_cmp_lg_u64 s[36:37], 0
	s_cbranch_scc1 .Lg80_w7
	s_waitcnt vmcnt(6)
	s_branch .Lg80_wd

.Lg80_wd:
	s_waitcnt lgkmcnt(0)
	s_barrier
	v_add_u32_e32 v104, s25, v103
	v_or_b32_e32 v100, s25, v45
	v_or_b32_e32 v101, s25, v95
	v_add_u32_e32 v128, v104, v45
	v_add_u32_e32 v131, v104, v95
	ds_read_b128 v[104:107], v100
	ds_read_b128 v[108:111], v100 offset:2048
	ds_read_b128 v[112:115], v100 offset:4096
	ds_read_b128 v[116:119], v100 offset:6144
	ds_read_b128 v[120:123], v100 offset:8192
	ds_read_b128 v[124:127], v128
	ds_read_b128 v[134:137], v128 offset:2048
	ds_read_b128 v[138:141], v101
	ds_read_b128 v[142:145], v101 offset:2048
	ds_read_b128 v[146:149], v101 offset:4096
	ds_read_b128 v[150:153], v101 offset:6144
	ds_read_b128 v[154:157], v101 offset:8192
	ds_read_b128 v[158:161], v131
	ds_read_b128 v[162:165], v131 offset:2048
	s_waitcnt lgkmcnt(7)
	s_add_u32 s42, s42, 0x80
	s_addc_u32 s43, s43, 0
	v_mfma_f32_16x16x32_bf16 v[36:39], v[124:127], v[104:107], v[36:39]
	v_mfma_f32_16x16x32_bf16 v[32:35], v[134:137], v[104:107], v[32:35]
	v_mfma_f32_16x16x32_bf16 v[28:31], v[124:127], v[108:111], v[28:31]
	v_mfma_f32_16x16x32_bf16 v[24:27], v[134:137], v[108:111], v[24:27]
	v_mfma_f32_16x16x32_bf16 v[20:23], v[124:127], v[112:115], v[20:23]
	v_mfma_f32_16x16x32_bf16 v[16:19], v[134:137], v[112:115], v[16:19]
	v_mfma_f32_16x16x32_bf16 v[12:15], v[124:127], v[116:119], v[12:15]
	v_mfma_f32_16x16x32_bf16 v[4:7], v[124:127], v[120:123], v[4:7]
	v_mfma_f32_16x16x32_bf16 v[0:3], v[134:137], v[120:123], v[0:3]
	v_mfma_f32_16x16x32_bf16 v[8:11], v[134:137], v[116:119], v[8:11]
	s_waitcnt lgkmcnt(0)
	s_barrier
	s_cmp_lt_u32 s24, 6
	s_cbranch_scc0 .Lg80_nd
	s_mov_b32 s28, s25
	v_add_u32_e32 v104, s28, v94
	v_lshl_add_u64 v[100:101], v[96:97], 0, s[42:43]
	s_mov_b64 s[44:45], 0xc65c080
	v_lshl_add_u64 v[106:107], v[100:101], 0, s[44:45]
	v_readfirstlane_b32 s44, v104
	s_mov_b32 m0, s44
	s_mov_b64 s[44:45], 0xc674080
	v_add_u32_e32 v105, 0x1000, v104
	global_load_lds_dwordx4 v[106:107], off
	v_lshl_add_u64 v[106:107], v[100:101], 0, s[44:45]
	v_readfirstlane_b32 s44, v105
	s_mov_b32 m0, s44
	s_nop 0
	global_load_lds_dwordx4 v[106:107], off
	s_and_saveexec_b64 s[44:45], s[36:37]
	s_cbranch_execz .Lg80i_noA3
	s_mov_b64 s[52:53], 0xc68c080
	v_add_u32_e32 v104, 0x2000, v104
	v_lshl_add_u64 v[100:101], v[100:101], 0, s[52:53]
	v_readfirstlane_b32 s52, v104
	s_mov_b32 m0, s52
	s_nop 0
	global_load_lds_dwordx4 v[100:101], off

.Lg80_nd:
	s_nop 0
	v_mfma_f32_16x16x32_bf16 v[36:39], v[158:161], v[138:141], v[36:39]
	v_mfma_f32_16x16x32_bf16 v[32:35], v[162:165], v[138:141], v[32:35]
	v_mfma_f32_16x16x32_bf16 v[28:31], v[158:161], v[142:145], v[28:31]
	v_mfma_f32_16x16x32_bf16 v[24:27], v[162:165], v[142:145], v[24:27]
	v_mfma_f32_16x16x32_bf16 v[20:23], v[158:161], v[146:149], v[20:23]
	v_mfma_f32_16x16x32_bf16 v[16:19], v[162:165], v[146:149], v[16:19]
	v_mfma_f32_16x16x32_bf16 v[12:15], v[158:161], v[150:153], v[12:15]
	v_mfma_f32_16x16x32_bf16 v[8:11], v[162:165], v[150:153], v[8:11]
	v_mfma_f32_16x16x32_bf16 v[4:7], v[158:161], v[154:157], v[4:7]
	v_mfma_f32_16x16x32_bf16 v[0:3], v[162:165], v[154:157], v[0:3]
	s_add_i32 s24, s24, 1
	s_xor_b32 s25, s25, 0x8000
	s_cmpk_lg_i32 s42, 0x400
	s_cbranch_scc1 .LBB0_89
	s_branch .LBB0_83
